# all seams XCD-local again; act/ycat aliasing across batches guarded by a counter: every workgroup counts its finished out-GEMMs (barrier word 121) and each wave of the next up-GEMM waits for all 256 b
# speedup vs baseline: 1.0071x; 1.0071x over previous
; __global__ void __launch_bounds__(512, 2) fwd_megakernel(Args args) {
;     ...
;         for (int mi = 0; mi < 12; ++mi) {
;             const int l = mi / 6, t = mi % 6;
;             const float* g; const float* u = nullptr; const float* ks = nullptr; int kind = 0, ldn, K, Np; bf16* WT = (bf16*)(ws + WS_W + (size_t)l * WL_SIZE);
;             if (t == 0)      { g = args.in[2] + (size_t)l * DM * DFF; u = args.in[3] + (size_t)l * DM * DFF; ks = args.in[1] + l * DM; kind = 1; ldn = DFF; K = DM; Np = NGU; WT += WL_GU1 / 2; }
;             else if (t == 1) { g = args.in[4] + (size_t)l * DFF * DM; ldn = DM; K = DFF; Np = DM; WT += WL_D1 / 2; }
;             else if (t == 2) { g = args.in[6] + (size_t)l * DM * DINP; ks = args.in[5] + l * DM; kind = 2; ldn = DINP; K = DM; Np = NPROJ; WT += WL_IN / 2; }
;             else if (t == 3) { g = args.in[21] + (size_t)l * DM * DM; ldn = DM; K = DM; Np = DM; WT += WL_OUT / 2; }
;             else if (t == 4) { g = args.in[23] + (size_t)l * DM * DFF; u = args.in[24] + (size_t)l * DM * DFF; ks = args.in[22] + l * DM; kind = 1; ldn = DFF; K = DM; Np = NGU; WT += WL_GU2 / 2; }
;             else             { g = args.in[25] + (size_t)l * DFF * DM; ldn = DM; K = DFF; Np = DM; WT += WL_D2 / 2; }
;             const int nitems = (K / 64) * (Np / 32);
;             for (int it = gw; it < nitems; it += NGW) transpose_item(kind, g, u, ldn, K, Np, ks, WT, scr, it, lane);
.LBB0_36:
	s_lshr_b32 s84, s79, 6
	s_mul_i32 s84, s84, s77
	v_readlane_b32 s6, v251, 61
	s_cmp_gt_u32 s75, 5
	s_cselect_b32 s7, 0x80, 0
	s_cselect_b32 s95, 6, 0
	s_sub_u32 s95, s75, s95
	s_lshl_b32 s95, s95, 2
	s_lshr_b32 s95, 0x60c160, s95
	s_and_b32 s95, s95, 15
	s_lshl_b32 s95, s95, 7
	s_add_u32 s7, s7, s95
	s_sub_u32 s7, s6, s7
	s_and_b32 s7, s7, 0x7ff
	s_cmpk_lg_u32 s82, 0x100
	s_cselect_b32 s6, s6, s7
	v_writelane_b32 v255, s6, 41
	s_cmp_ge_i32 s6, s84
	v_readlane_b32 s7, v251, 62
	s_cbranch_scc1 .LBB0_20
	v_cvt_f32_u32_e32 v0, s77
	s_lshl_b32 s0, s78, 1
	s_lshl_b32 s6, s78, 2
	s_lshl_b32 s10, s78, 3
	v_rcp_iflag_f32_e32 v0, v0
	s_lshl_b32 s18, s78, 4
	s_lshl_b32 s36, s78, 5
	s_cmp_lg_u64 s[72:73], 0
	v_mul_f32_e32 v0, 0x4f7ffffe, v0
	v_cvt_u32_f32_e32 v0, v0
	v_mov_b32_e32 v13, v9
	s_cselect_b64 s[68:69], -1, 0
	v_lshl_add_u64 v[16:17], s[70:71], 0, v[12:13]
	s_sub_i32 s70, 0, s77
	v_readfirstlane_b32 s71, v0
	s_mul_i32 s70, s70, s71
	s_mul_hi_u32 s70, s71, s70
	s_add_i32 s85, s71, s70
	s_lshl_b32 s70, s77, 5
	s_sub_i32 s86, 0, s70
	v_readlane_b32 s70, v255, 41
	v_mov_b32_e32 v11, v9
	v_readlane_b32 s71, v251, 62
	v_lshl_add_u64 v[14:15], s[72:73], 0, v[10:11]
	s_mov_b32 s72, s70
	s_lshl_b32 s87, s70, 5
	v_readlane_b32 s71, v251, 63
	s_lshl_b32 s70, s77, 4
	s_mov_b32 s7, s1
	s_mul_i32 s8, s78, 6
	s_mov_b32 s9, s1
	s_mov_b32 s11, s1
	s_mul_i32 s12, s78, 10
	s_mov_b32 s13, s1
	s_mul_i32 s14, s78, 12
	s_mov_b32 s15, s1
	s_mul_i32 s16, s78, 14
	s_mov_b32 s17, s1
	s_mov_b32 s19, s1
	s_mul_i32 s20, s78, 18
	s_mov_b32 s21, s1
	s_mul_i32 s22, s78, 20
	s_mov_b32 s23, s1
	s_mul_i32 s24, s78, 22
	s_mov_b32 s25, s1
	s_mul_i32 s26, s78, 24
	s_mov_b32 s27, s1
	s_mul_i32 s28, s78, 26
	s_mov_b32 s29, s1
	s_mul_i32 s30, s78, 28
	s_mov_b32 s31, s1
	s_mul_i32 s34, s78, 30
	s_mov_b32 s35, s1
	s_mov_b32 s37, s1
	s_mul_i32 s38, s78, 34
	s_mov_b32 s39, s1
	s_mul_i32 s40, s78, 36
	s_mov_b32 s41, s1
	s_mul_i32 s42, s78, 38
	s_mov_b32 s43, s1
	s_mul_i32 s44, s78, 40
	s_mov_b32 s45, s1
	s_mul_i32 s46, s78, 42
	s_mov_b32 s47, s1
	s_mul_i32 s48, s78, 44
	s_mov_b32 s49, s1
	s_mul_i32 s50, s78, 46
	s_mov_b32 s51, s1
	s_mul_i32 s52, s78, 48
	s_mov_b32 s53, s1
	s_mul_i32 s54, s78, 50
	s_mov_b32 s55, s1
	s_mul_i32 s56, s78, 52
	s_mov_b32 s57, s1
	s_mul_i32 s58, s78, 54
	s_mov_b32 s59, s1
	s_mul_i32 s60, s78, 56
	s_mov_b32 s61, s1
	s_mul_i32 s62, s78, 58
	s_mov_b32 s63, s1
	s_mul_i32 s64, s78, 60
	s_mov_b32 s65, s1
	s_mul_i32 s66, s78, 62
	s_mov_b32 s67, s1
	s_lshl_b32 s88, s71, 5
	s_sub_i32 s89, 0, s70
	s_lshl_b32 s90, s72, 4
	s_lshl_b32 s91, s71, 4
	s_mov_b32 s92, s72
	s_branch .LBB0_41

; #define LAS __attribute__((address_space(3)))
; __global__ void __launch_bounds__(512, 2) fwd_megakernel(Args args) {
;     ...
;     volatile LAS unsigned* bst = (volatile LAS unsigned*)(lds + 147440);
;     if (threadIdx.x < 4) bst[threadIdx.x] = 0u;
;     __syncthreads();
;     (void)xcd_barrier_post((unsigned*)(args.ws + WS_BAR), bst);
;     ...
;     const int wave = __builtin_amdgcn_readfirstlane((int)threadIdx.x >> 6);
;     const int G = gridDim.x, bid = blockIdx.x;
;     const int gw = bid * 8 + wave, NGW = G * 8;
;     unsigned char* ws = args.ws;
;     float* ssq = (float*)(ws + WS_SSQ);     float* mss_g = (float*)(ws + WS_MSSQ);   float* mss_a = mss_g + (size_t)2 * MTOK * 4;   float* dtraw = (float*)(ws + WS_DTRAW); float* CD = (float*)(ws + WS_CD);
;     bf16* sguW = (bf16*)(ws + WS_SGUW);
;     bf16* xb = (bf16*)(ws + WS_XB); float* ST = args.out;     bf16* actb = (bf16*)(ws + WS_ACT); bf16* Yg = (bf16*)(ws + WS_YG); bf16* ycat = (bf16*)(ws + WS_YCAT);
;     bf16* PV = (bf16*)(ws + WS_PV); bf16* proj = (bf16*)(ws + WS_PROJ);
.LBB0_144:
	s_or_b64 exec, exec, s[0:1]
	s_mov_b32 s32, 1
	s_add_u32 s0, s80, 0x400000
	s_addc_u32 s1, s81, 0
	v_writelane_b32 v252, s0, 3
	v_readlane_b32 s54, v251, 0
	v_readlane_b32 s8, v251, 1
	v_writelane_b32 v252, s1, 4
	s_add_u32 s0, s80, 0x600000
	s_addc_u32 s1, s81, 0
	v_writelane_b32 v252, s0, 5
	v_readlane_b32 s9, v251, 2
	v_readlane_b32 s10, v251, 3
	v_writelane_b32 v252, s1, 6
	s_add_u32 s0, s80, 0x12000000
	s_addc_u32 s1, s81, 0
	s_add_u32 s79, s80, 0x300000
	v_writelane_b32 v252, s0, 7
	s_addc_u32 s17, s81, 0
	v_readlane_b32 s11, v251, 4
	v_writelane_b32 v252, s1, 8
	s_add_u32 s0, s80, 0x500000
	s_addc_u32 s1, s81, 0
	s_add_u32 s84, s80, 0xa000000
	s_addc_u32 s85, s81, 0
	s_add_u32 s18, s80, 0xe000000
	v_writelane_b32 v252, s0, 9
	s_addc_u32 s19, s81, 0
	v_readlane_b32 s12, v251, 5
	v_writelane_b32 v252, s1, 10
	s_add_u32 s0, s80, 0x15000000
	s_addc_u32 s1, s81, 0
	v_writelane_b32 v252, s0, 11
	s_cmpk_lt_i32 s54, 0xb00
	v_readlane_b32 s13, v251, 6
	v_writelane_b32 v252, s1, 12
	s_cselect_b64 s[0:1], -1, 0
	v_writelane_b32 v252, s0, 13
	s_ashr_i32 s53, s54, 31
	s_ashr_i32 s2, s82, 31
	v_writelane_b32 v252, s1, 14
	s_lshr_b32 s0, s53, 29
	s_add_i32 s1, s54, s0
	s_ashr_i32 s0, s1, 3
	s_and_b32 s1, s1, -8
	s_sub_i32 s1, s54, s1
	v_writelane_b32 v252, s2, 15
	s_add_u32 s2, s80, 0x10200
	s_addc_u32 s3, s81, 0
	v_writelane_b32 v252, s2, 16
	v_readlane_b32 s14, v251, 7
	v_readlane_b32 s15, v251, 8
	v_writelane_b32 v252, s3, 17
	s_add_u32 s2, s80, 0x10400
	s_addc_u32 s3, s81, 0
	v_writelane_b32 v252, s2, 18
	s_mov_b64 s[8:9], s[12:13]
	s_mov_b64 s[10:11], s[14:15]
	v_writelane_b32 v252, s3, 19
	s_add_u32 s2, s80, 0x10500
	s_addc_u32 s3, s81, 0
	v_writelane_b32 v252, s2, 20
	v_mov_b32_e32 v193, 0
	v_mov_b32_e32 v240, 0x2000
	v_writelane_b32 v252, s3, 21
	s_add_u32 s2, s80, 0x10600
	s_addc_u32 s3, s81, 0
	v_writelane_b32 v252, s2, 22
	v_mov_b32_e32 v241, 1
	v_mov_b32_e32 v194, 0x358637bd
	v_writelane_b32 v252, s3, 23
	s_add_u32 s2, s80, 0x10700
	s_addc_u32 s3, s81, 0
	v_writelane_b32 v252, s2, 24
	v_mov_b32_e32 v250, 0x3ecc95a3
	v_mov_b32_e32 v223, 0xc0135761
	v_writelane_b32 v252, s3, 25
	s_add_u32 s2, s80, 0x10800
	s_addc_u32 s3, s81, 0
	v_writelane_b32 v252, s2, 26
	v_mov_b32_e32 v224, 0x80000
	v_mov_b32_e32 v225, 0x20000
	v_writelane_b32 v252, s3, 27
	s_add_u32 s2, s80, 0x10900
	s_addc_u32 s3, s81, 0
	v_writelane_b32 v252, s2, 28
	v_mov_b32_e32 v226, 0x40000
	v_mov_b32_e32 v227, 0x60000
	v_writelane_b32 v252, s3, 29
	s_add_u32 s2, s80, 0x10a00
	s_addc_u32 s3, s81, 0
	v_writelane_b32 v252, s2, 30
	v_mbcnt_hi_u32_b32 v228, -1, v56
	v_mov_b32_e32 v200, 0x3f317218
	v_writelane_b32 v252, s3, 31
	s_add_u32 s2, s80, 0x10b00
	s_addc_u32 s3, s81, 0
	v_writelane_b32 v252, s2, 32
	v_mov_b32_e32 v222, 0x7f800000
	v_mov_b32_e32 v229, 0x7fc00000
	v_writelane_b32 v252, s3, 33
	s_add_u32 s2, s80, 0x10c00
	s_addc_u32 s3, s81, 0
	v_writelane_b32 v252, s2, 34
	v_mov_b32_e32 v242, 0xff800000
	v_mov_b32_e32 v218, v193
	v_writelane_b32 v252, s3, 35
	s_add_u32 s2, s80, 0x10d00
	s_addc_u32 s3, s81, 0
	v_writelane_b32 v252, s2, 36
	v_mov_b32_e32 v219, v193
	s_mov_b32 s59, 0
	v_writelane_b32 v252, s3, 37
	s_add_u32 s2, s80, 0x10e00
	s_addc_u32 s3, s81, 0
	v_writelane_b32 v252, s2, 38
	s_waitcnt lgkmcnt(0)
	s_barrier
	v_writelane_b32 v252, s3, 39
	s_add_u32 s2, s80, 0x10f00
	s_addc_u32 s3, s81, 0
	v_writelane_b32 v252, s2, 40
	s_nop 1
	v_writelane_b32 v252, s3, 41
	s_add_u32 s2, s80, 0x11000
	s_addc_u32 s3, s81, 0
	v_writelane_b32 v252, s2, 42
	s_nop 1
	v_writelane_b32 v252, s3, 43
	s_add_u32 s2, s80, 0x11100
	s_addc_u32 s3, s81, 0
	v_writelane_b32 v252, s2, 44
	s_nop 1
	v_writelane_b32 v252, s3, 45
	s_add_u32 s2, s80, 0x11200
	s_addc_u32 s3, s81, 0
	v_writelane_b32 v252, s2, 46
	s_nop 1
	v_writelane_b32 v252, s3, 47
	s_add_u32 s2, s80, 0x11300
	s_addc_u32 s3, s81, 0
	v_writelane_b32 v252, s2, 48
	s_nop 1
	v_writelane_b32 v252, s3, 49
	s_add_u32 s2, s80, 0x13400
	s_addc_u32 s3, s81, 0
	v_writelane_b32 v252, s2, 50
	s_nop 1
	v_writelane_b32 v252, s3, 51
	s_add_u32 s2, s80, 0x13500
	s_addc_u32 s3, s81, 0
	v_writelane_b32 v252, s2, 52
	s_cmpk_lt_i32 s54, 0x200
	s_nop 0
	v_writelane_b32 v252, s3, 53
	s_cselect_b64 s[2:3], -1, 0
	v_writelane_b32 v252, s2, 54
	s_nop 1
	v_writelane_b32 v252, s3, 55
	s_lshl_b32 s2, s1, 6
	s_cmpk_lt_i32 s54, 0x500
	s_cselect_b64 s[4:5], -1, 0
	v_writelane_b32 v252, s4, 56
	s_cmpk_lt_i32 s52, 0x800
	s_nop 0
	v_writelane_b32 v252, s5, 57
	s_cselect_b64 s[4:5], -1, 0
	v_writelane_b32 v252, s4, 58
	s_cmpk_lt_u32 s74, 0x180
	s_nop 0
	v_writelane_b32 v252, s5, 59
	s_cselect_b64 s[4:5], -1, 0
	v_writelane_b32 v252, s4, 60
	s_nop 1
	v_writelane_b32 v252, s5, 61
	s_nop 0
	v_readlane_b32 s16, v252, 0
	s_lshl_b32 s4, s16, 1
	s_add_i32 s20, s4, -12
	s_lshl_b32 s86, s16, 4
	s_lshl_b32 s3, s16, 6
	s_add_u32 s6, s10, s3
	v_writelane_b32 v252, s3, 62
	s_addc_u32 s7, s11, 0
	v_writelane_b32 v252, s6, 63
	s_cmpk_lt_i32 s54, 0x100
	s_mul_i32 s3, s16, 0x1500
	v_writelane_b32 v254, s7, 0
	s_cselect_b64 s[6:7], -1, 0
	v_writelane_b32 v254, s6, 1
	s_add_i32 s3, s3, 0
	s_add_i32 s3, s3, 0x11c00
	v_writelane_b32 v254, s7, 2
	v_writelane_b32 v254, s3, 3
	s_lshl_b32 s3, s16, 9
	s_add_i32 s3, s3, 0
	s_add_i32 s5, s3, 0x22000
	v_writelane_b32 v254, s5, 4
	s_add_i32 s3, s3, 0x22800
	v_writelane_b32 v254, s3, 5
	s_lshl_b32 s3, s16, 5
	v_writelane_b32 v254, s3, 6
	s_add_i32 s3, s3, 0
	v_writelane_b32 v254, s3, 7
	s_lshl_b32 s3, s16, 11
	s_or_b32 s5, s16, 1
	s_cmpk_gt_u32 s74, 0x17f
	s_cselect_b64 s[94:95], -1, 0
	s_cmpk_gt_u32 s74, 0xff
	v_writelane_b32 v254, s3, 8
	s_cselect_b64 s[92:93], -1, 0
	s_cmp_lt_i32 s1, 0
	s_mul_i32 s3, s1, 0x41
	s_cselect_b32 s6, s3, s2
;     __host__ __device__ bool next(int i, Unit& u) const {
;         const long L = (long)i * G + c; if (L >= nwg) return false;
;         int wgid = (int)L; { const int q = nwg / NXCD, r = nwg % NXCD, xcd = wgid % NXCD, off = wgid / NXCD; wgid = (xcd < r ? xcd * (q + 1) : r * (q + 1) + (xcd - r) * q) + off; }
;         const int nig = WGM * nN, gid = wgid / nig, fm = gid * WGM, gsz = (nM - fm) < WGM ? (nM - fm) : WGM;
;         u.pm = fm + ((wgid % nig) % gsz); u.pn = (wgid % nig) / gsz; return true;
;     }
	s_movk_i32 s2, 0x161
	s_cselect_b32 s2, s2, 0x160
	s_mul_i32 s2, s1, s2
	s_movk_i32 s3, 0xa1
	s_cselect_b32 s7, s3, 0xa0
	s_add_i32 s2, s2, s0
	s_mul_hi_i32 s3, s2, 0x2e8ba2e9
	s_lshr_b32 s8, s3, 31
	s_ashr_i32 s3, s3, 5
	s_add_i32 s3, s3, s8
	s_mul_i32 s8, s3, 0xb0
	s_sub_i32 s2, s2, s8
	s_bfe_u32 s8, s2, 0x3001c
	s_add_i32 s8, s2, s8
	s_and_b32 s9, s8, 0xfff8
	s_sub_i32 s2, s2, s9
	s_lshl_b32 s3, s3, 3
	s_sext_i32_i16 s8, s8
	s_sext_i32_i16 s2, s2
	s_add_i32 s10, s3, s2
	s_ashr_i32 s2, s8, 3
	v_writelane_b32 v254, s2, 9
	s_lshr_b32 s2, s8, 3
	s_bfe_i64 s[2:3], s[2:3], 0x100000
	s_lshl_b64 s[2:3], s[2:3], 19
	v_writelane_b32 v254, s2, 10
	s_ashr_i32 s11, s10, 31
	s_mul_i32 s1, s1, s7
	v_writelane_b32 v254, s3, 11
	s_mov_b32 s2, s10
	v_writelane_b32 v254, s2, 12
	s_nop 1
	v_writelane_b32 v254, s3, 13
	s_lshl_b64 s[2:3], s[10:11], 19
	s_add_u32 s2, s88, s2
	s_addc_u32 s3, s89, s3
	s_add_u32 s8, s2, 0x40000
	v_writelane_b32 v254, s2, 14
	s_addc_u32 s9, s3, 0
	s_add_i32 s1, s1, s0
	v_writelane_b32 v254, s3, 15
	s_add_i32 s2, s6, s0
	s_ashr_i32 s3, s2, 31
	s_lshr_b32 s3, s3, 27
	s_add_i32 s3, s2, s3
	s_mul_hi_i32 s0, s1, 0x66666667
	s_and_b32 s6, s3, 0xffe0
	s_lshr_b32 s7, s0, 31
	s_ashr_i32 s0, s0, 5
	s_sub_i32 s2, s2, s6
	s_add_i32 s0, s0, s7
	s_bfe_i32 s6, s2, 0x80000
	s_mul_i32 s7, s0, 0x50
	s_bfe_u32 s6, s6, 0x3000c
	s_sub_i32 s1, s1, s7
	v_writelane_b32 v254, s8, 16
	s_add_i32 s6, s2, s6
	s_bfe_i32 s7, s1, 0x80000
	v_writelane_b32 v254, s9, 17
	s_and_b32 s8, s6, 0xf8
	s_bfe_u32 s7, s7, 0x3000c
	s_sub_i32 s2, s2, s8
	s_add_i32 s7, s1, s7
	s_ashr_i32 s3, s3, 5
	s_and_b32 s8, s7, 0xf8
	s_lshl_b32 s3, s3, 3
	s_sext_i32_i8 s2, s2
	s_sub_i32 s1, s1, s8
	s_add_i32 s8, s3, s2
	s_bfe_i32 s2, s7, 0x80000
	s_lshl_b32 s0, s0, 3
	s_sext_i32_i16 s2, s2
	s_sext_i32_i8 s1, s1
	s_add_i32 s10, s0, s1
	s_ashr_i32 s0, s2, 3
	v_writelane_b32 v254, s0, 18
	s_lshr_b32 s0, s2, 3
	s_bfe_i64 s[0:1], s[0:1], 0x100000
	s_bfe_i32 s6, s6, 0x80000
	s_lshl_b64 s[0:1], s[0:1], 19
	s_sext_i32_i16 s6, s6
	v_writelane_b32 v254, s0, 19
	s_mov_b32 s2, s10
	s_ashr_i32 s11, s10, 31
	v_writelane_b32 v254, s1, 20
	s_ashr_i32 s0, s6, 3
	v_writelane_b32 v254, s0, 21
	v_writelane_b32 v254, s2, 22
	s_lshr_b32 s0, s6, 3
	s_nop 0
	v_writelane_b32 v254, s3, 23
	s_lshl_b64 s[2:3], s[10:11], 19
	s_add_u32 s2, s88, s2
	s_addc_u32 s3, s89, s3
	s_add_u32 s6, s2, 0x40000
	v_writelane_b32 v254, s2, 24
	s_addc_u32 s7, s3, 0
	s_lshl_b32 s1, s20, 9
	v_writelane_b32 v254, s3, 25
	v_writelane_b32 v254, s6, 26
	s_add_i32 s2, 0, 0x19800
	s_add_i32 s3, s2, s1
	v_writelane_b32 v254, s7, 27
	v_writelane_b32 v254, s20, 28
	v_writelane_b32 v254, s3, 29
	s_add_i32 s3, 0, 0x1a000
	s_add_i32 s1, s3, s1
	v_writelane_b32 v254, s1, 30
	s_add_i32 s1, s4, -11
	v_writelane_b32 v254, s1, 31
	s_lshl_b32 s1, s1, 9
	v_writelane_b32 v254, s2, 32
	s_add_i32 s2, s2, s1
	v_writelane_b32 v254, s2, 33
	v_writelane_b32 v254, s3, 34
	s_add_i32 s1, s3, s1
	v_writelane_b32 v254, s1, 35
	s_add_i32 s1, s86, 0x60
	v_writelane_b32 v254, s1, 36
	s_add_i32 s1, s86, 0x70
	s_add_i32 s87, s86, 16
	s_add_i32 s91, s86, 32
	s_add_i32 s90, s86, 48
	s_add_i32 s96, s86, 64
	s_add_i32 s97, s86, 0x50
	v_writelane_b32 v254, s1, 37
	s_add_i32 s1, s86, 0x80
	s_cmpk_gt_u32 s74, 0x1ff
	v_writelane_b32 v254, s1, 38
	s_cselect_b64 s[2:3], -1, 0
	v_writelane_b32 v254, s2, 39
	s_cmpk_gt_u32 s74, 0x1bf
	s_nop 0
	v_writelane_b32 v254, s3, 40
	s_cselect_b64 s[2:3], -1, 0
	v_writelane_b32 v254, s2, 41
	s_cmpk_gt_u32 s74, 0x13f
	s_nop 0
	v_writelane_b32 v254, s3, 42
	s_cselect_b64 s[2:3], -1, 0
	v_writelane_b32 v254, s2, 43
	s_cmpk_gt_u32 s74, 0xbf
	s_nop 0
	v_writelane_b32 v254, s3, 44
	s_cselect_b64 s[2:3], -1, 0
	s_cmpk_gt_u32 s74, 0x7f
	v_writelane_b32 v254, s2, 45
	s_cselect_b64 s[56:57], -1, 0
	s_cmp_gt_u32 s74, 63
	v_writelane_b32 v254, s3, 46
	s_cselect_b64 s[2:3], -1, 0
	v_writelane_b32 v254, s2, 47
	s_nop 1
	v_writelane_b32 v254, s3, 48
	s_add_u32 s2, s80, 0x420000
	s_addc_u32 s3, s81, 0
	v_writelane_b32 v254, s2, 49
	s_nop 1
	v_writelane_b32 v254, s3, 50
	s_add_u32 s2, s80, 0x440000
	s_addc_u32 s3, s81, 0
	v_writelane_b32 v254, s2, 51
	s_nop 1
	v_writelane_b32 v254, s3, 52
	s_add_u32 s2, s80, 0x460000
	s_addc_u32 s3, s81, 0
	v_writelane_b32 v254, s2, 53
	s_cmp_gt_u32 s5, 2
	s_nop 0
	v_writelane_b32 v254, s3, 54
	s_cselect_b64 s[2:3], -1, 0
	v_writelane_b32 v254, s2, 55
	s_cmp_gt_u32 s5, 4
	s_nop 0
	v_writelane_b32 v254, s3, 56
	s_cselect_b64 s[2:3], -1, 0
	v_writelane_b32 v254, s2, 57
	s_cmp_gt_u32 s5, 6
	s_nop 0
	v_writelane_b32 v254, s3, 58
	s_cselect_b64 s[2:3], -1, 0
	v_writelane_b32 v254, s2, 59
	s_ashr_i32 s9, s8, 31
	s_bfe_i64 s[0:1], s[0:1], 0x100000
	v_writelane_b32 v254, s3, 60
	s_mul_i32 s3, s8, 0x160000
	s_mul_hi_i32 s2, s8, 0x160000
	s_add_u32 s4, s84, s3
	s_addc_u32 s5, s85, s2
	s_add_u32 s2, s4, 0xb0000
	v_writelane_b32 v254, s4, 61
	s_addc_u32 s3, s5, 0
	s_lshl_b64 s[0:1], s[0:1], 19
	v_writelane_b32 v254, s5, 62
	v_writelane_b32 v254, s2, 63
	s_mov_b64 s[4:5], -1
	s_nop 0
	v_writelane_b32 v253, s3, 0
	v_writelane_b32 v253, s0, 1
	s_nop 1
	v_writelane_b32 v253, s1, 2
	s_mov_b32 s0, s8
	v_writelane_b32 v253, s0, 3
	s_nop 1
	v_writelane_b32 v253, s1, 4
	s_lshl_b64 s[0:1], s[8:9], 19
	s_add_u32 s2, s18, s0
	v_writelane_b32 v253, s18, 5
	s_mul_i32 s0, s83, s82
	s_mul_i32 s0, s0, s33
	v_writelane_b32 v253, s19, 6
	s_addc_u32 s3, s19, s1
	v_writelane_b32 v253, s0, 7
	s_add_u32 s0, s2, 0x40000
	v_writelane_b32 v253, s2, 8
	s_addc_u32 s1, s3, 0
	s_mov_b32 s83, s17
	v_writelane_b32 v253, s3, 9
	v_writelane_b32 v253, s0, 10
	s_movk_i32 s33, 0x230
	s_mov_b32 s2, 0
	v_writelane_b32 v253, s1, 11
	s_lshl_b32 s0, s54, 7
	v_writelane_b32 v253, s0, 12
	s_add_i32 s0, s0, s86
	v_writelane_b32 v253, s0, 13
	s_lshl_b32 s0, s82, 7
	v_writelane_b32 v253, s0, 14
	s_add_u32 s0, s80, 0x1d80200
	v_writelane_b32 v253, s0, 15
	s_addc_u32 s0, s81, 0
	s_bitcmp1_b32 s54, 0
	v_writelane_b32 v253, s0, 16
	s_cselect_b64 s[0:1], -1, 0
	v_writelane_b32 v253, s0, 17
	s_bitcmp1_b32 s82, 0
	s_nop 0
	v_writelane_b32 v253, s1, 18
	s_mul_i32 s0, s16, 0x210
	v_writelane_b32 v253, s0, 19
	s_mov_b32 s0, s82
	v_writelane_b32 v253, s0, 20
	s_cselect_b64 s[0:1], -1, 0
	v_writelane_b32 v253, s0, 21
	s_lshl_b32 s74, s82, 5
	s_lshl_b32 s75, s82, 4
	v_writelane_b32 v253, s1, 22
	s_add_i32 s0, 0, 0x23ff0
	v_writelane_b32 v253, s0, 23
	s_add_i32 s0, 0, 0x23ff4
	v_writelane_b32 v253, s0, 24
	s_add_i32 s0, 0, 0x9200
	v_writelane_b32 v253, s0, 25
	v_writelane_b32 v253, s53, 26
	v_writelane_b32 v253, s74, 27
	v_writelane_b32 v253, s75, 28
	v_writelane_b32 v253, s79, 29
	v_writelane_b32 v253, s83, 30
	v_writelane_b32 v253, s97, 31
	v_writelane_b32 v253, s56, 32
	s_mov_b64 s[0:1], 0x80
	s_nop 0
	v_writelane_b32 v253, s57, 33
	v_writelane_b32 v253, s90, 34
	v_writelane_b32 v253, s96, 35
	v_writelane_b32 v253, s87, 36
	s_branch .LBB0_146

; #define LAS __attribute__((address_space(3)))
; DI bool lane0_() { return (opaque_tid() & 63) == 0; }
; #define GRID_SYNC() do { XcdBarrier b_; b_.bar = (unsigned*)(args.ws + WS_BAR); b_.x = xb_xcc_id(); b_.st = (volatile LAS unsigned*)(lds + 147440); xcd_barrier(b_); } while (0)
; __global__ void __launch_bounds__(512, 2) fwd_megakernel(Args args) {
;     ...
;             for (int rep_ = 0; rep_ < UPREP; ++rep_) {
;                 pg8::Gemm g{xb, Wl + (half ? WL_GU2 : WL_GU1) / 2, MTOK, NGU, DM}; pg8::StaticOrder S; S.init(MTOK, NGU, G, bid);
;                 if (lane0_()) *(LAS int*)((LAS float*)(lds + 135168) + wave * 132 + 128) = -1;
;                 EpiSwiglu E{actb, ssq + (size_t)(3 * layer + 2 * half) * MTOK * 4, (LAS float*)(lds + 135168)};
;                 pg8::gemm_phase<EpiSwiglu, pg8::StaticOrder, true, true>(lds, g, S, E);
;             }
;             GRID_SYNC();
.LBB0_164:
	s_bitcmp1_b32 s32, 0
	s_cbranch_scc1 .Lguard_done
	s_add_u32 s98, s80, 0x101e4
	s_addc_u32 s99, s81, 0
	s_andn2_b32 s26, s32, 1
	s_mov_b32 s27, 0
.Lguard_spin:
	global_load_dword v140, v193, s[98:99] sc1
	s_waitcnt vmcnt(0)
	v_cmp_le_u32_e32 vcc, s26, v140
	s_cbranch_vccnz .Lguard_ok
	s_sleep 1
	s_add_i32 s27, s27, 1
	s_cmp_lt_u32 s27, 0x8000
	s_cbranch_scc1 .Lguard_spin
.Lguard_ok:
	s_or_b32 s32, s32, 1

; #define LAS __attribute__((address_space(3)))
; #define GRID_SYNC() do { XcdBarrier b_; b_.bar = (unsigned*)(args.ws + WS_BAR); b_.x = xb_xcc_id(); b_.st = (volatile LAS unsigned*)(lds + 147440); xcd_barrier(b_); } while (0)
; __global__ void __launch_bounds__(512, 2) fwd_megakernel(Args args) {
;     ...
;             {
;                 pg8::Gemm g{ycat, Wl + WL_OUT / 2, MTOK, DM, DM}; pg8::StaticOrder S; S.init(MTOK, DM, G, bid);
;                 EpiResid E{xb, ssq + (size_t)(3 * layer + 2) * MTOK * 4, 1.0f, (LAS float*)(lds + 131072)};
;                 pg8::gemm_phase<EpiResid, pg8::StaticOrder, true, true>(lds, g, S, E);
;             }
;             GRID_SYNC();
.LBB0_1234:
	s_getreg_b32 s2, hwreg(HW_REG_XCC_ID, 0, 4)
	s_waitcnt vmcnt(0)
	s_waitcnt lgkmcnt(0)
	s_barrier
	s_and_b32 s32, s32, -2
	s_add_u32 s32, s32, 0x100
	s_and_saveexec_b64 s[4:5], s[76:77]
	s_cbranch_execz .Lfb9_skip
	s_add_u32 s8, s80, 0x101e4
	s_addc_u32 s9, s81, 0
	v_mov_b32_e32 v0, 0
	v_mov_b32_e32 v1, 1
	global_atomic_add v0, v1, s[8:9]
	v_mov_b32_e32 v0, 0x23ff8
	ds_read_b32 v2, v0
	s_waitcnt lgkmcnt(0)
	v_readfirstlane_b32 s3, v2
	s_cmp_eq_u32 s3, 1
	s_cbranch_scc0 .LBB0_1235
	v_readlane_b32 s3, v251, 0
	s_and_b32 s6, s3, 7
	s_lshl_b32 s6, s6, 5
	s_add_u32 s8, s80, 0x10040
	s_addc_u32 s9, s81, 0
	s_add_u32 s8, s8, s6
	s_addc_u32 s9, s9, 0
	v_mov_b32_e32 v0, 0
	v_mov_b32_e32 v1, 1
	global_atomic_add v2, v0, v1, s[8:9] sc0
	s_waitcnt vmcnt(0)
	v_readfirstlane_b32 s3, v2
	s_lshr_b32 s7, s3, 5
	s_add_i32 s7, s7, 1
	s_and_b32 s3, s3, 31
	s_cmp_eq_u32 s3, 31
	s_cbranch_scc0 .Lfb9_spin0
	global_atomic_add v0, v1, s[8:9] offset:4
	s_branch .Lfb9_rel
